# grid barrier spin loops poll with s_sleep 0 instead of s_sleep 1 (tighter detection latency on both barrier levels)
# speedup vs baseline: 1.0052x; 1.0052x over previous
; __device__ __forceinline__ unsigned xb_ld(unsigned* p)              { return __hip_atomic_load(p, __ATOMIC_RELAXED, __HIP_MEMORY_SCOPE_AGENT); }
; #define XB_SPIN(cond, bar) do { unsigned _sp = 0; while (cond) { __builtin_amdgcn_s_sleep(1); \
;     if ((++_sp & 255u) == 0u) { if (xb_ld(&(bar)[XB_TMO])) break; if (_sp > XB_SPIN_CAP) { atomicAdd(&(bar)[XB_TMO], 1u); break; } } } } while (0)
; __device__ __forceinline__ void xcd_barrier(const XcdBarrier& b) {
;     ...
;             XB_SPIN(xb_ld(&bar[XB_XGEN(b.x)]) == gen, bar);
.LBB0_351:
	s_and_b32 s12, s16, 0xff
	s_mov_b64 s[10:11], -1
	s_cmp_lg_u32 s12, 0
	s_mov_b64 s[14:15], -1
	s_sleep 0
	s_cbranch_scc1 .LBB0_354
	v_readlane_b32 s12, v252, 2
	v_readlane_b32 s13, v252, 3
	s_nop 4
	global_load_dword v2, v1, s[12:13] sc1
	s_waitcnt vmcnt(0)
	v_cmp_eq_u32_e32 vcc, 0, v2
	s_cbranch_vccnz .LBB0_356
	s_mov_b64 s[14:15], 0
	s_mov_b64 s[12:13], -1
